# dilation-merge loop: the three OG loads issued together with the LSE loads (one memory round trip per item instead of two)
# speedup vs baseline: 1.0044x; 1.0044x over previous
; #define GAS __attribute__((address_space(1)))
; __device__ __forceinline__ float bflo(unsigned w) { return __uint_as_float(w << 16); }
; __device__ __forceinline__ float bfhi(unsigned w) { return __uint_as_float(w & 0xffff0000u); }
; __device__ __forceinline__ u32x4 pack8(f32x4 v0, f32x4 v1) { u32x4 w; w.x = cvt_pk_bf16(v0[0], v0[1]); w.y = cvt_pk_bf16(v0[2], v0[3]); w.z = cvt_pk_bf16(v1[0], v1[1]); w.w = cvt_pk_bf16(v1[2], v1[3]); return w; }
; __global__ void __launch_bounds__(512, 2) fwd_kernel(Args args) {
;     ...
;                 for (int it = bx * 512 + tid; it < CH * 32; it += G * 512) { const int row = it >> 5, j = (it >> 3) & 3, d8 = (it & 7) * 8;
;                     const float l0 = LSEb[row * 12 + j], l1 = LSEb[row * 12 + 4 + j], l2 = LSEb[row * 12 + 8 + j]; const float mx = fmaxf(l0, fmaxf(l1, l2));
;                     float w0 = __expf(l0 - mx), w1 = __expf(l1 - mx), w2 = __expf(l2 - mx); const float inv = 1.0f / (w0 + w1 + w2); w0 *= inv; w1 *= inv; w2 *= inv;
;                     const bf16_t* p0 = OGb + ((size_t)row * 12 + j) * 64 + d8; const u32x4 q0 = *(const GAS u32x4*)p0, q1 = *(const GAS u32x4*)(p0 + 4 * 64), q2 = *(const GAS u32x4*)(p0 + 8 * 64);
;                     const f32x4 a0 = (f32x4){bflo(q0.x), bfhi(q0.x), bflo(q0.y), bfhi(q0.y)} * w0 + (f32x4){bflo(q1.x), bfhi(q1.x), bflo(q1.y), bfhi(q1.y)} * w1 + (f32x4){bflo(q2.x), bfhi(q2.x), bflo(q2.y), bfhi(q2.y)} * w2;
;                     const f32x4 a1 = (f32x4){bflo(q0.z), bfhi(q0.z), bflo(q0.w), bfhi(q0.w)} * w0 + (f32x4){bflo(q1.z), bfhi(q1.z), bflo(q1.w), bfhi(q1.w)} * w1 + (f32x4){bflo(q2.z), bfhi(q2.z), bflo(q2.w), bfhi(q2.w)} * w2;
;                     *(GAS u32x4*)(OBb + (size_t)row * 256 + j * 64 + d8) = pg8::pack8(a0, a1); }
.LBB0_72:
	v_ashrrev_i32_e32 v14, 5, v8
	v_bfe_u32 v17, v8, 3, 2
	v_mad_i64_i32 v[0:1], s[18:19], v14, 12, 0
	v_or_b32_e32 v2, v0, v17
	v_ashrrev_i32_e32 v3, 31, v2
	v_lshl_add_u64 v[4:5], v[2:3], 2, s[22:23]
	flat_load_dword v0, v[4:5]
	v_add_u32_e32 v4, 4, v2
	v_ashrrev_i32_e32 v5, 31, v4
	v_lshl_add_u64 v[4:5], v[4:5], 2, s[22:23]
	flat_load_dword v3, v[4:5]
	v_add_u32_e32 v4, 8, v2
	v_ashrrev_i32_e32 v5, 31, v4
	v_lshl_add_u64 v[4:5], v[4:5], 2, s[22:23]
	flat_load_dword v4, v[4:5]
	v_and_b32_e32 v6, 56, v9
	v_lshlrev_b32_e32 v168, 1, v6
	v_ashrrev_i32_e32 v15, 31, v14
	v_add_u32_e32 v8, s4, v8
	v_add_u32_e32 v9, s13, v9
	v_mov_b32_e32 v38, v2
	v_mov_b32_e32 v39, v1
	v_lshlrev_b64 v[38:39], 7, v[38:39]
	v_lshl_add_u64 v[38:39], s[20:21], 0, v[38:39]
	v_lshl_add_u64 v[38:39], v[38:39], 0, v[168:169]
	global_load_dwordx4 v[26:29], v[38:39], off
	global_load_dwordx4 v[30:33], v[38:39], off offset:512
	global_load_dwordx4 v[34:37], v[38:39], off offset:1024
	s_waitcnt vmcnt(0) lgkmcnt(0)
	v_max3_f32 v5, v0, v3, v4
	v_sub_f32_e32 v0, v0, v5
	v_sub_f32_e32 v3, v3, v5
	v_mul_f32_e32 v0, 0x3fb8aa3b, v0
	v_mul_f32_e32 v3, 0x3fb8aa3b, v3
	v_sub_f32_e32 v4, v4, v5
	v_exp_f32_e32 v0, v0
	v_exp_f32_e32 v3, v3
	v_mul_f32_e32 v4, 0x3fb8aa3b, v4
	v_exp_f32_e32 v4, v4
	v_add_f32_e32 v5, v0, v3
	v_add_f32_e32 v5, v4, v5
	v_div_scale_f32 v7, s[18:19], v5, v5, 1.0
	v_rcp_f32_e32 v10, v7
	s_mov_b32 s18, 0x7ffff
	v_fma_f32 v11, -v7, v10, 1.0
	v_fmac_f32_e32 v10, v11, v10
	v_div_scale_f32 v11, vcc, 1.0, v5, 1.0
	v_mul_f32_e32 v12, v11, v10
	v_fma_f32 v13, -v7, v12, v11
	v_fmac_f32_e32 v12, v13, v10
	v_fma_f32 v7, -v7, v12, v11
	v_div_fmas_f32 v7, v7, v10, v12
	v_div_fixup_f32 v5, v7, v5, 1.0
	v_mul_f32_e32 v18, v3, v5
	v_mov_b32_e32 v3, v1
	v_mul_f32_e32 v16, v0, v5
	v_lshlrev_b64 v[0:1], 7, v[2:3]
	v_lshl_add_u64 v[0:1], s[20:21], 0, v[0:1]
	v_lshl_add_u64 v[10:11], v[0:1], 0, v[168:169]
	v_mul_f32_e32 v20, v4, v5
	v_mov_b64_e32 v[0:1], v[26:27]
	v_mov_b64_e32 v[2:3], v[28:29]
	v_mov_b64_e32 v[4:5], v[30:31]
	v_mov_b64_e32 v[6:7], v[32:33]
	s_nop 0
	v_mov_b64_e32 v[10:11], v[34:35]
	v_mov_b64_e32 v[12:13], v[36:37]
	v_cmp_lt_i32_e32 vcc, s18, v8
	s_or_b64 s[16:17], vcc, s[16:17]
	s_waitcnt vmcnt(2)
	v_lshlrev_b32_e32 v22, 16, v0
	s_waitcnt vmcnt(1)
	v_lshlrev_b32_e32 v24, 16, v4
	v_and_b32_e32 v25, 0xffff0000, v4
	v_lshlrev_b32_e32 v4, 16, v5
	v_and_b32_e32 v5, 0xffff0000, v5
	v_and_b32_e32 v23, 0xffff0000, v0
	v_lshlrev_b32_e32 v0, 16, v1
	v_and_b32_e32 v1, 0xffff0000, v1
	v_pk_mul_f32 v[4:5], v[18:19], v[4:5] op_sel_hi:[0,1]
	v_pk_mul_f32 v[24:25], v[18:19], v[24:25] op_sel_hi:[0,1]
	v_pk_fma_f32 v[22:23], v[16:17], v[22:23], v[24:25] op_sel_hi:[0,1,1]
	v_pk_fma_f32 v[0:1], v[16:17], v[0:1], v[4:5] op_sel_hi:[0,1,1]
	s_waitcnt vmcnt(0)
	v_lshlrev_b32_e32 v4, 16, v10
	v_and_b32_e32 v5, 0xffff0000, v10
	v_lshlrev_b32_e32 v10, 16, v11
	v_and_b32_e32 v11, 0xffff0000, v11
	v_pk_fma_f32 v[10:11], v[20:21], v[10:11], v[0:1] op_sel_hi:[0,1,1]
	v_pk_fma_f32 v[0:1], v[20:21], v[4:5], v[22:23] op_sel_hi:[0,1,1]
	v_lshlrev_b32_e32 v22, 16, v6
	v_and_b32_e32 v23, 0xffff0000, v6
	v_lshlrev_b32_e32 v6, 16, v7
	v_and_b32_e32 v7, 0xffff0000, v7
	v_lshlrev_b32_e32 v4, 16, v2
	v_and_b32_e32 v5, 0xffff0000, v2
	v_lshlrev_b32_e32 v2, 16, v3
	v_and_b32_e32 v3, 0xffff0000, v3
	v_pk_mul_f32 v[6:7], v[18:19], v[6:7] op_sel_hi:[0,1]
	v_pk_mul_f32 v[18:19], v[18:19], v[22:23] op_sel_hi:[0,1]
	v_pk_fma_f32 v[4:5], v[16:17], v[4:5], v[18:19] op_sel_hi:[0,1,1]
	v_pk_fma_f32 v[2:3], v[16:17], v[2:3], v[6:7] op_sel_hi:[0,1,1]
	v_lshlrev_b32_e32 v6, 16, v12
	v_and_b32_e32 v7, 0xffff0000, v12
	v_lshlrev_b32_e32 v12, 16, v13
	v_and_b32_e32 v13, 0xffff0000, v13
	v_pk_fma_f32 v[12:13], v[20:21], v[12:13], v[2:3] op_sel_hi:[0,1,1]
	v_pk_fma_f32 v[2:3], v[20:21], v[6:7], v[4:5] op_sel_hi:[0,1,1]
	v_lshlrev_b64 v[4:5], 9, v[14:15]
	v_lshl_add_u64 v[4:5], s[40:41], 0, v[4:5]
	v_lshlrev_b32_e32 v6, 7, v17
	v_mov_b32_e32 v7, v169
	v_lshl_add_u64 v[4:5], v[4:5], 0, v[6:7]
	v_lshl_add_u64 v[4:5], v[4:5], 0, v[168:169]
	v_cvt_pk_bf16_f32 v0, v0, v1
	v_cvt_pk_bf16_f32 v1, v10, v11
	v_cvt_pk_bf16_f32 v2, v2, v3
	v_cvt_pk_bf16_f32 v3, v12, v13
	global_store_dwordx4 v[4:5], v[0:3], off
	s_andn2_b64 exec, exec, s[16:17]
	s_cbranch_execnz .LBB0_72
